# streamers start directly with their sample FOX stream unit (prompt-SB-first removed now that the stream chain is the P2 critical path)
# baseline (speedup 1.0000x reference)
; #define LDS_AS __attribute__((address_space(3)))
; #define QUEUE_LOOP(QI, NUNITS, BODY) \
;         for (;;) { \
;             __syncthreads(); \
;             if (tid == 0) *sunit = (int)atomicAdd(p.ctrl + cq + (QI), 1u); \
;             __syncthreads(); \
;             const int u = *sunit; \
;             if (u >= (NUNITS)) break; \
;             BODY; \
;         }
; __global__ void __launch_bounds__(512, 2) hymba_mega(Params p) {
;     ...
;     for (int rep = 0; rep < 1 + DUP_P2; ++rep) {
;         const int cq = rep * 64;
;         LDS_AS int* sunit = (LDS_AS int*)((LDS_AS char*)smem + SM_UNIT_OFF);
;     ...
;         const bool streamer = ((blockIdx.x >> 3) & 3) == 0;
;         for (int ph = 0; ph < 4; ++ph) {
;             const int qi = streamer ? (ph == 0 ? 0 : ph == 1 ? 2 : ph == 2 ? 1 : 3) : (ph == 0 ? 1 : ph == 1 ? 0 : ph == 2 ? 2 : 3);
;             if (qi == 0) { QUEUE_LOOP(0, NU_SF, sample_unit<1>(p, u / NSPLIT, u % NSPLIT, smem, cq)) }
.LBB0_400:
	s_or_b64 exec, exec, s[0:1]
	v_mov_b32_e32 v251, 0x180
	global_load_dwordx2 v[254:255], v251, s[56:57] sc0 sc1
	s_and_b32 s0, s2, 24
	s_cmp_lg_u32 s0, 0
	s_mov_b32 s0, 0x20040
	s_cselect_b64 s[12:13], -1, 0
	v_bfe_u32 v141, v0, 20, 10
	v_bfe_u32 v143, v0, 10, 10
	s_add_i32 s63, s0, 0x100
	s_mov_b32 s0, 0x20044
	v_mbcnt_lo_u32_b32 v0, -1, 0
	s_mov_b32 s11, 0
	v_mov_b32_e32 v131, 0
	s_movk_i32 s62, 0x100
	s_movk_i32 s66, 0x21f
	s_movk_i32 s67, 0x1000
	s_movk_i32 s88, 0x1010
	s_mov_b64 s[14:15], 0x10000
	s_mov_b64 s[16:17], 0x20000
	s_mov_b64 s[20:21], 0x30000
	s_movk_i32 s89, 0x90
	s_mov_b32 s90, 0xc2400000
	s_movk_i32 s91, 0x1200
	s_mov_b64 s[22:23], 0x1000
	s_mov_b32 s92, 0x12000
	s_mov_b32 s93, 0xf149f2ca
	s_movk_i32 s94, 0x2100
	s_add_i32 s95, s0, 0x100
	s_mov_b32 s96, 0x10000
	s_mov_b64 s[24:25], 0x10900
	s_mov_b64 s[26:27], 0x10940
	s_mov_b64 s[28:29], 0x1c00
	v_mov_b32_e32 v145, 0xff800000
	v_mbcnt_hi_u32_b32 v174, -1, v0
	v_mov_b32_e32 v147, 0x100
	v_mov_b32_e32 v175, 0x42000
	s_mov_b32 s97, 0
	s_and_b64 vcc, exec, s[12:13]
	s_cbranch_vccnz .Lstr_s97
	s_mov_b32 s97, 0
